# grid-barrier set-up poll: 16 counter loads issued together and summed after one wait instead of load-wait-add per counter
# speedup vs baseline: 1.0035x; 1.0035x over previous
; __device__ __forceinline__ unsigned xb_ld(unsigned* p)              { return __hip_atomic_load(p, __ATOMIC_RELAXED, __HIP_MEMORY_SCOPE_AGENT); }
; __device__ __forceinline__ void xcd_barrier_complete(unsigned* bar, unsigned x, unsigned& nloc, unsigned& nx) {
;     const unsigned G = gridDim.x * gridDim.y * gridDim.z;
;     unsigned sum, cnt, mine, sp = 0u;
;     for (;;) {
;         sum = 0u; cnt = 0u; mine = 0u;
; #pragma unroll
;         for (unsigned j = 0; j < 16; ++j) { const unsigned c = xb_ld(&bar[XB_XCNT(j)]); sum += c; cnt += (c > 0u) ? 1u : 0u; mine = (j == x) ? c : mine; }
;         if (sum == G) break;
;         __builtin_amdgcn_s_sleep(1);
;         if ((++sp & 255u) == 0u) { if (xb_ld(&bar[XB_TMO])) break; if (sp > XB_SPIN_CAP) { atomicAdd(&bar[XB_TMO], 1u); break; } }
;     }
.LBB0_1572:
	v_readlane_b32 s4, v252, 25
	v_readlane_b32 s5, v252, 26
	global_load_dword v0, v1, s[22:23] sc1
	s_mov_b64 s[8:9], -1
	s_waitcnt lgkmcnt(0)
	s_nop 1
	global_load_dword v2, v1, s[4:5] sc1
	v_readlane_b32 s4, v252, 27
	v_readlane_b32 s5, v252, 28
	s_nop 0
	s_nop 0
	s_nop 2
	global_load_dword v3, v1, s[4:5] sc1
	v_readlane_b32 s4, v252, 29
	v_readlane_b32 s5, v252, 30
	s_nop 0
	s_nop 0
	s_nop 2
	global_load_dword v4, v1, s[4:5] sc1
	v_readlane_b32 s4, v252, 31
	v_readlane_b32 s5, v252, 32
	s_nop 0
	s_nop 0
	s_nop 2
	global_load_dword v5, v1, s[4:5] sc1
	v_readlane_b32 s4, v252, 33
	v_readlane_b32 s5, v252, 34
	s_nop 0
	s_nop 0
	s_nop 2
	global_load_dword v6, v1, s[4:5] sc1
	v_readlane_b32 s4, v252, 35
	v_readlane_b32 s5, v252, 36
	s_nop 0
	s_nop 0
	s_nop 2
	global_load_dword v7, v1, s[4:5] sc1
	v_readlane_b32 s4, v252, 37
	v_readlane_b32 s5, v252, 38
	s_nop 0
	s_nop 0
	s_nop 2
	global_load_dword v8, v1, s[4:5] sc1
	v_readlane_b32 s4, v252, 39
	v_readlane_b32 s5, v252, 40
	s_nop 0
	s_nop 0
	s_nop 2
	global_load_dword v9, v1, s[4:5] sc1
	v_readlane_b32 s4, v252, 41
	v_readlane_b32 s5, v252, 42
	s_nop 0
	s_nop 0
	s_nop 2
	global_load_dword v10, v1, s[4:5] sc1
	v_readlane_b32 s4, v252, 43
	v_readlane_b32 s5, v252, 44
	s_nop 0
	s_nop 0
	s_nop 2
	global_load_dword v11, v1, s[4:5] sc1
	v_readlane_b32 s4, v252, 45
	v_readlane_b32 s5, v252, 46
	s_nop 0
	s_nop 0
	s_nop 2
	global_load_dword v12, v1, s[4:5] sc1
	v_readlane_b32 s4, v252, 47
	v_readlane_b32 s5, v252, 48
	s_nop 0
	s_nop 0
	s_nop 2
	global_load_dword v13, v1, s[4:5] sc1
	v_readlane_b32 s4, v252, 49
	v_readlane_b32 s5, v252, 50
	s_nop 0
	s_nop 0
	s_nop 2
	global_load_dword v14, v1, s[4:5] sc1
	v_readlane_b32 s4, v252, 51
	v_readlane_b32 s5, v252, 52
	s_nop 0
	s_nop 0
	s_nop 2
	global_load_dword v15, v1, s[4:5] sc1
	v_readlane_b32 s4, v252, 53
	v_readlane_b32 s5, v252, 54
	s_nop 0
	s_nop 0
	s_nop 2
	global_load_dword v16, v1, s[4:5] sc1
	s_mov_b64 s[4:5], -1
	s_waitcnt vmcnt(0)
	v_add_u32_e32 v17, v2, v0
	v_add_u32_e32 v17, v17, v3
	v_add_u32_e32 v17, v17, v4
	v_add_u32_e32 v17, v17, v5
	v_add_u32_e32 v17, v17, v6
	v_add_u32_e32 v17, v17, v7
	v_add_u32_e32 v17, v17, v8
	v_add_u32_e32 v17, v17, v9
	v_add_u32_e32 v17, v17, v10
	v_add_u32_e32 v17, v17, v11
	v_add_u32_e32 v17, v17, v12
	v_add_u32_e32 v17, v17, v13
	v_add_u32_e32 v17, v17, v14
	v_add_u32_e32 v17, v17, v15
	v_add_u32_e32 v17, v17, v16
	v_cmp_eq_u32_e32 vcc, s47, v17
	s_cbranch_vccnz .LBB0_1571
	s_and_b32 s4, s3, 0xff
	s_cmp_eq_u32 s4, 0
	s_mov_b64 s[4:5], -1
	s_mov_b64 s[10:11], -1
	s_sleep 1
	s_cbranch_scc1 .LBB0_1576
	s_and_b64 vcc, exec, s[10:11]
	s_cbranch_vccz .LBB0_1571
